# LDS-DMA loads use SGPR base + per-thread 32-bit VGPR offset (no per-stage 64-bit address VALU) in the FFN1/PROJ/FFN2/WOUT loops
# speedup vs baseline: 1.0069x; 1.0069x over previous
; DI int TIDX() { int t = threadIdx.x; asm volatile("" : "+v"(t)); return t; }
; #define XCD_LOOP(Mx, ntn) const int xcd_ = BIDX() & 7; for (int u_ = BIDX() >> 3; u_ < (Mx) * (ntn); u_ += (int)(gridDim.x >> 3))
; DI void gemm_tile_deep(const h16* __restrict__ A, int lda, const h16* __restrict__ B, int ldb, int K, f32x16 (&acc)[2][2], h16* sm) {
;   const int tid = TIDX(), lane = tid & 63, w = tid >> 6, wm = w >> 1, wn = w & 1, r = lane & 31, hh = lane >> 5;
;   const unsigned ao = (unsigned)(tid >> 3) * (unsigned)lda + (unsigned)(tid & 7) * 8u;
;   const unsigned bo = (unsigned)(tid >> 3) * (unsigned)ldb + (unsigned)(tid & 7) * 8u;
;   const h16* ag = A;
;   const h16* bg = B;
;   u32x4 ra0[4], rb0[4], ra1[4], rb1[4];
; #pragma unroll
;   for (int i = 0; i < 4; ++i) {
;     ra0[i] = *(const u32x4*)(ag + (ao + (unsigned)i * 32u * (unsigned)lda));
;     rb0[i] = *(const u32x4*)(bg + (bo + (unsigned)i * 32u * (unsigned)ldb));
;   }
;   ag += 64; bg += 64;
; #pragma unroll
;   for (int i = 0; i < 4; ++i) {
;     ra1[i] = *(const u32x4*)(ag + (ao + (unsigned)i * 32u * (unsigned)lda));
;     rb1[i] = *(const u32x4*)(bg + (bo + (unsigned)i * 32u * (unsigned)ldb));
;   }
;   const int nk = K >> 6;
;   const int wofs = (tid >> 3) * LSTR + (tid & 7) * 8;
; DI void phase_gemm_plain(const h16* A, int lda, const h16* Bt, int K, h16* C, int ldc, int mt0, int mt1, int ntn, char* smem) {
;   const int Mx = (mt1 - mt0) >> 3;
;   XCD_LOOP(Mx, ntn) {
;     int mt_, nt_;
;     tile_map(u_, Mx, ntn, xcd_, mt_, nt_);
;     const int m0 = (mt0 + mt_) * 128, n0 = nt_ * 128;
;     f32x16 acc[2][2];
;     zero_acc(acc);
;     gemm_tile_deep(A + (size_t)m0 * lda, lda, Bt + (size_t)n0 * K, K, K, acc, (h16*)smem);
.LBB0_58:
	s_ashr_i32 s8, s15, 31
	s_lshr_b32 s8, s8, 26
	s_add_i32 s8, s15, s8
	s_ashr_i32 s9, s8, 6
	s_lshl_b32 s9, s9, 3
	s_sub_i32 s10, s20, s9
	s_min_i32 s10, s10, 8
	s_abs_i32 s11, s10
	v_cvt_f32_u32_e32 v0, s11
	s_sub_i32 s23, 0, s11
	s_andn2_b32 s8, s8, 63
	s_sub_i32 s8, s15, s8
	v_rcp_iflag_f32_e32 v0, v0
	s_abs_i32 s12, s8
	s_xor_b32 s13, s8, s10
	s_ashr_i32 s13, s13, 31
	v_mul_f32_e32 v0, 0x4f7ffffe, v0
	v_cvt_u32_f32_e32 v0, v0
	v_mov_b32_e32 v18, v203
	v_mov_b32_e32 v7, v1
	v_readfirstlane_b32 s24, v0
	s_mul_i32 s23, s23, s24
	s_mul_hi_u32 s23, s24, s23
	s_add_i32 s24, s24, s23
	s_mul_hi_u32 s23, s12, s24
	s_mul_i32 s24, s23, s11
	s_sub_i32 s12, s12, s24
	s_add_i32 s25, s23, 1
	s_sub_i32 s24, s12, s11
	s_cmp_ge_u32 s12, s11
	s_cselect_b32 s23, s25, s23
	s_cselect_b32 s12, s24, s12
	s_add_i32 s24, s23, 1
	s_cmp_ge_u32 s12, s11
	s_cselect_b32 s11, s24, s23
	s_xor_b32 s11, s11, s13
	s_sub_i32 s12, s11, s13
	s_add_i32 s9, s9, s21
	s_mul_i32 s10, s10, s12
	s_add_i32 s9, s9, s8
	s_sub_i32 s8, s9, s10
	s_lshl_b32 s24, s8, 7
	s_lshl_b32 s23, s12, 7
	s_mul_i32 s8, s8, 0xb0000
	s_mul_hi_i32 s9, s24, 0x1600
	s_add_u32 s10, s18, s8
	s_addc_u32 s11, s19, s9
	s_mul_i32 s12, s12, 0xb0000
	s_add_u32 s8, s16, s12
	v_ashrrev_i32_e32 v19, 3, v18
	s_movk_i32 s12, 0xb00
	v_lshlrev_b32_e32 v2, 3, v18
	v_mul_lo_u32 v0, v19, s12
	v_and_b32_e32 v20, 56, v2
	v_bfe_u32 v21, v18, 4, 3
	v_lshlrev_b32_e32 v21, 3, v21
	v_xor_b32_e32 v20, v20, v21
	v_or_b32_e32 v0, v0, v20
	s_mul_hi_i32 s9, s23, 0x1600
	v_add_u32_e32 v6, 0x42000, v0
	s_addc_u32 s9, s17, s9
	v_add_u32_e32 v2, 0x16000, v0
	v_mov_b32_e32 v3, v1
	v_add_u32_e32 v4, 0x2c000, v0
	v_mov_b32_e32 v5, v1
	s_waitcnt vmcnt(0)
	v_lshlrev_b64 v[146:147], 1, v[6:7]
	v_lshl_add_u64 v[6:7], s[8:9], 0, v[146:147]
	v_lshlrev_b64 v[148:149], 1, v[4:5]
	v_lshlrev_b64 v[150:151], 1, v[2:3]
	v_lshlrev_b64 v[152:153], 1, v[0:1]
	v_lshl_add_u64 v[8:9], s[10:11], 0, v[146:147]
	v_lshl_add_u64 v[4:5], s[8:9], 0, v[148:149]
	v_lshl_add_u64 v[10:11], s[10:11], 0, v[148:149]
	v_lshl_add_u64 v[2:3], s[8:9], 0, v[150:151]
	v_lshl_add_u64 v[12:13], s[10:11], 0, v[150:151]
	v_lshl_add_u64 v[14:15], s[8:9], 0, v[152:153]
	v_lshl_add_u64 v[16:17], s[10:11], 0, v[152:153]
	v_readfirstlane_b32 s38, v203
	s_nop 3
	s_lshr_b32 s38, s38, 6
	s_lshl_b32 s38, s38, 10
	v_and_b32_e32 v140, 31, v203
	v_bfe_u32 v141, v203, 5, 1
	v_bfe_u32 v142, v203, 1, 3
	v_xor_b32_e32 v141, v141, v142
	v_lshlrev_b32_e32 v141, 4, v141
	v_lshl_or_b32 v140, v140, 7, v141
	v_lshrrev_b32_e32 v142, 7, v203
	v_lshl_add_u32 v130, v142, 13, v140
	v_bfe_u32 v142, v203, 6, 1
	v_lshl_add_u32 v134, v142, 13, v140
	v_xor_b32_e32 v131, 0x20, v130
	v_xor_b32_e32 v135, 0x20, v134
	v_xor_b32_e32 v132, 0x40, v130
	v_xor_b32_e32 v136, 0x40, v134
	v_xor_b32_e32 v133, 0x60, v130
	v_xor_b32_e32 v137, 0x60, v134
	s_add_u32 m0, s38, 0x0
	s_nop 0
	global_load_lds_dwordx4 v152, s[10:11]
	s_add_u32 m0, s38, 0x4000
	s_nop 0
	global_load_lds_dwordx4 v152, s[8:9]
	s_add_u32 m0, s38, 0x1000
	s_nop 0
	global_load_lds_dwordx4 v150, s[10:11]
	s_add_u32 m0, s38, 0x5000
	s_nop 0
	global_load_lds_dwordx4 v150, s[8:9]
	s_add_u32 m0, s38, 0x2000
	s_nop 0
	global_load_lds_dwordx4 v148, s[10:11]
	s_add_u32 m0, s38, 0x6000
	s_nop 0
	global_load_lds_dwordx4 v148, s[8:9]
	s_add_u32 m0, s38, 0x3000
	s_nop 0
	global_load_lds_dwordx4 v146, s[10:11]
	s_add_u32 m0, s38, 0x7000
	s_nop 0
	global_load_lds_dwordx4 v146, s[8:9]
	s_add_u32 s8, s8, 0x80
	s_addc_u32 s9, s9, 0
	s_add_u32 s10, s10, 0x80
	s_addc_u32 s11, s11, 0
	v_mov_b32_e32 v2, 0
	s_mov_b32 s22, 0
	v_mov_b32_e32 v3, v2
	v_mov_b32_e32 v4, v2
	v_mov_b32_e32 v5, v2
	v_mov_b32_e32 v6, v2
	v_mov_b32_e32 v7, v2
	v_mov_b32_e32 v8, v2
	v_mov_b32_e32 v9, v2
	v_mov_b32_e32 v10, v2
	v_mov_b32_e32 v11, v2
	v_mov_b32_e32 v12, v2
	v_mov_b32_e32 v13, v2
	v_mov_b32_e32 v14, v2
	v_mov_b32_e32 v15, v2
	v_mov_b32_e32 v16, v2
	v_mov_b32_e32 v17, v2
	v_mov_b32_e32 v18, v2
	v_mov_b32_e32 v19, v2
	v_mov_b32_e32 v20, v2
	v_mov_b32_e32 v21, v2
	v_mov_b32_e32 v22, v2
	v_mov_b32_e32 v23, v2
	v_mov_b32_e32 v24, v2
	v_mov_b32_e32 v25, v2
	v_mov_b32_e32 v26, v2
	v_mov_b32_e32 v27, v2
	v_mov_b32_e32 v28, v2
	v_mov_b32_e32 v29, v2
	v_mov_b32_e32 v30, v2
	v_mov_b32_e32 v31, v2
	v_mov_b32_e32 v32, v2
	v_mov_b32_e32 v33, v2
	v_mov_b32_e32 v34, v2
	v_mov_b32_e32 v35, v2
	v_mov_b32_e32 v36, v2
	v_mov_b32_e32 v37, v2
	v_mov_b32_e32 v38, v2
	v_mov_b32_e32 v39, v2
	v_mov_b32_e32 v40, v2
	v_mov_b32_e32 v41, v2
	v_mov_b32_e32 v42, v2
	v_mov_b32_e32 v43, v2
	v_mov_b32_e32 v44, v2
	v_mov_b32_e32 v45, v2
	v_mov_b32_e32 v46, v2
	v_mov_b32_e32 v47, v2
	v_mov_b32_e32 v48, v2
	v_mov_b32_e32 v49, v2
	v_mov_b32_e32 v50, v2
	v_mov_b32_e32 v51, v2
	v_mov_b32_e32 v52, v2
	v_mov_b32_e32 v53, v2
	v_mov_b32_e32 v54, v2
	v_mov_b32_e32 v55, v2
	v_mov_b32_e32 v56, v2
	v_mov_b32_e32 v57, v2
	v_mov_b32_e32 v58, v2
	v_mov_b32_e32 v59, v2
	v_mov_b32_e32 v60, v2
	v_mov_b32_e32 v61, v2
	v_mov_b32_e32 v62, v2
	v_mov_b32_e32 v63, v2
	v_mov_b32_e32 v64, v2
	v_mov_b32_e32 v65, v2
	s_waitcnt vmcnt(0)
	s_barrier
.Lf2_stage0:
	ds_read_b128 v[66:69], v130 offset:0
	ds_read_b128 v[70:73], v130 offset:4096
	ds_read_b128 v[74:77], v134 offset:16384
	ds_read_b128 v[78:81], v134 offset:20480
	ds_read_b128 v[82:85], v131 offset:0
	ds_read_b128 v[86:89], v131 offset:4096
	ds_read_b128 v[90:93], v135 offset:16384
	ds_read_b128 v[94:97], v135 offset:20480
	ds_read_b128 v[98:101], v132 offset:0
	ds_read_b128 v[102:105], v132 offset:4096
	ds_read_b128 v[106:109], v136 offset:16384
	ds_read_b128 v[110:113], v136 offset:20480
	s_cmp_ge_u32 s22, 43
	s_cbranch_scc1 .Lf2_nl0
	s_add_u32 m0, s38, 0x8000
	s_nop 0
	global_load_lds_dwordx4 v152, s[10:11]
	s_add_u32 m0, s38, 0xc000
	s_nop 0
	global_load_lds_dwordx4 v152, s[8:9]
	s_add_u32 m0, s38, 0x9000
	s_nop 0
	global_load_lds_dwordx4 v150, s[10:11]
	s_add_u32 m0, s38, 0xd000
	s_nop 0
	global_load_lds_dwordx4 v150, s[8:9]
	s_add_u32 m0, s38, 0xa000
	s_nop 0
	global_load_lds_dwordx4 v148, s[10:11]
	s_add_u32 m0, s38, 0xe000
	s_nop 0
	global_load_lds_dwordx4 v148, s[8:9]
	s_add_u32 m0, s38, 0xb000
	s_nop 0
	global_load_lds_dwordx4 v146, s[10:11]
	s_add_u32 m0, s38, 0xf000
	s_nop 0
	global_load_lds_dwordx4 v146, s[8:9]
	s_add_u32 s8, s8, 0x80
	s_addc_u32 s9, s9, 0
	s_add_u32 s10, s10, 0x80
	s_addc_u32 s11, s11, 0

.Lf2_stage1:
	ds_read_b128 v[66:69], v130 offset:32768
	ds_read_b128 v[70:73], v130 offset:36864
	ds_read_b128 v[74:77], v134 offset:49152
	ds_read_b128 v[78:81], v134 offset:53248
	ds_read_b128 v[82:85], v131 offset:32768
	ds_read_b128 v[86:89], v131 offset:36864
	ds_read_b128 v[90:93], v135 offset:49152
	ds_read_b128 v[94:97], v135 offset:53248
	ds_read_b128 v[98:101], v132 offset:32768
	ds_read_b128 v[102:105], v132 offset:36864
	ds_read_b128 v[106:109], v136 offset:49152
	ds_read_b128 v[110:113], v136 offset:53248
	s_cmp_ge_u32 s22, 43
	s_cbranch_scc1 .Lf2_nl1
	s_add_u32 m0, s38, 0x0
	s_nop 0
	global_load_lds_dwordx4 v152, s[10:11]
	s_add_u32 m0, s38, 0x4000
	s_nop 0
	global_load_lds_dwordx4 v152, s[8:9]
	s_add_u32 m0, s38, 0x1000
	s_nop 0
	global_load_lds_dwordx4 v150, s[10:11]
	s_add_u32 m0, s38, 0x5000
	s_nop 0
	global_load_lds_dwordx4 v150, s[8:9]
	s_add_u32 m0, s38, 0x2000
	s_nop 0
	global_load_lds_dwordx4 v148, s[10:11]
	s_add_u32 m0, s38, 0x6000
	s_nop 0
	global_load_lds_dwordx4 v148, s[8:9]
	s_add_u32 m0, s38, 0x3000
	s_nop 0
	global_load_lds_dwordx4 v146, s[10:11]
	s_add_u32 m0, s38, 0x7000
	s_nop 0
	global_load_lds_dwordx4 v146, s[8:9]
	s_add_u32 s8, s8, 0x80
	s_addc_u32 s9, s9, 0
	s_add_u32 s10, s10, 0x80
	s_addc_u32 s11, s11, 0

; DI int TIDX() { int t = threadIdx.x; asm volatile("" : "+v"(t)); return t; }
; #define XCD_LOOP_W(Mt, ntn) const int xcd_ = BIDX() & 7; const int Mx_ = ((Mt) + 7) >> 3; for (int u_ = BIDX() >> 3; u_ < Mx_ * (ntn); u_ += (int)(gridDim.x >> 3))
; template <class BR>
; DI void gemm_tile_w(const h16* __restrict__ A, int lda, const h16* __restrict__ B, int ldb, BR brow, int K, f32x16 (&acc)[4][2], h16* sm) {
;   const int tid = TIDX(), lane = tid & 63, w = tid >> 6, wm = w >> 1, wn = w & 1, r = lane & 31, hh = lane >> 5;
;   const unsigned ao = (unsigned)(tid >> 2) * (unsigned)lda + (unsigned)(tid & 3) * 8u;
;   const unsigned bo0 = (unsigned)brow(tid >> 2) * (unsigned)ldb + (unsigned)(tid & 3) * 8u;
;   const unsigned bo1 = (unsigned)brow((tid >> 2) + 64) * (unsigned)ldb + (unsigned)(tid & 3) * 8u;
;   const h16* ag = A;
;   const h16* bg = B;
;   u32x4 ra0[4], rb0[2], ra1[4], rb1[2];
; #pragma unroll
;   for (int i = 0; i < 4; ++i) ra0[i] = *(const u32x4*)(ag + (ao + (unsigned)i * 64u * (unsigned)lda));
;   rb0[0] = *(const u32x4*)(bg + bo0);
;   rb0[1] = *(const u32x4*)(bg + bo1);
;   ag += 32; bg += 32;
; #pragma unroll
;   for (int i = 0; i < 4; ++i) ra1[i] = *(const u32x4*)(ag + (ao + (unsigned)i * 64u * (unsigned)lda));
;   rb1[0] = *(const u32x4*)(bg + bo0);
;   rb1[1] = *(const u32x4*)(bg + bo1);
;   const int nk = K >> 5;
;   const int wofs = (tid >> 2) * LS2 + (tid & 3) * 8;
; DI void phase_ffn1(const P& p, int l, int hf, char* smem) {
;     ...
;   XCD_LOOP_W(Mt, 44) {
;     int mt_, nt_;
;     tile_map(u_, Mx_, 44, xcd_, mt_, nt_);
;     if (mt_ >= Mt) continue;
;     const int m0 = mt0 * 128 + mt_ * 256, c0 = nt_ * 64;
;     f32x16 acc[4][2];
;     zero_acc_w(acc);
;     gemm_tile_w(h2 + (size_t)m0 * 1024, 1024, W, 1024,
;                 [&](int rr) { const int q = rr & 63; return ((q >> 5) ? 2816 : 0) + c0 + (rr >> 6) * 32 + (q & 31); }, 1024, acc, (h16*)smem);
.LBB0_71:
	s_mul_hi_i32 s12, s22, 0x2e8ba2e9
	s_lshr_b32 s13, s12, 31
	s_ashr_i32 s12, s12, 6
	s_add_i32 s12, s12, s13
	s_lshl_b32 s14, s12, 3
	s_sub_i32 s13, s21, s14
	s_min_i32 s15, s13, 8
	s_abs_i32 s13, s15
	v_cvt_f32_u32_e32 v0, s13
	s_sub_i32 s18, 0, s13
	s_mulk_i32 s12, 0xfea0
	s_add_i32 s12, s12, s22
	v_rcp_iflag_f32_e32 v0, v0
	s_abs_i32 s16, s12
	s_xor_b32 s17, s12, s15
	s_ashr_i32 s17, s17, 31
	v_mul_f32_e32 v0, 0x4f7ffffe, v0
	v_cvt_u32_f32_e32 v0, v0
	s_nop 0
	v_readfirstlane_b32 s19, v0
	s_mul_i32 s18, s18, s19
	s_mul_hi_u32 s18, s19, s18
	s_add_i32 s19, s19, s18
	s_mul_hi_u32 s18, s16, s19
	s_mul_i32 s19, s18, s13
	s_sub_i32 s16, s16, s19
	s_add_i32 s26, s18, 1
	s_sub_i32 s19, s16, s13
	s_cmp_ge_u32 s16, s13
	s_cselect_b32 s18, s26, s18
	s_cselect_b32 s16, s19, s16
	s_add_i32 s19, s18, 1
	s_cmp_ge_u32 s16, s13
	s_cselect_b32 s13, s19, s18
	s_xor_b32 s13, s13, s17
	s_sub_i32 s13, s13, s17
	s_add_i32 s14, s14, s38
	s_mul_i32 s15, s15, s13
	s_add_i32 s14, s14, s12
	s_sub_i32 s12, s14, s15
	s_cmp_ge_i32 s12, s20
	s_cbranch_scc1 .LBB0_70
	v_mov_b32_e32 v18, v203
	s_lshl_b32 s26, s13, 6
	s_lshl_b32 s12, s12, 8
	v_ashrrev_i32_e32 v19, 2, v18
	v_bfe_i32 v2, v18, 7, 1
	v_and_b32_e32 v2, 0xb00, v2
	v_lshrrev_b32_e32 v3, 3, v18
	v_and_or_b32 v4, v19, 31, s26
	v_and_b32_e32 v3, 0x3fffe0, v3
	v_add_u32_e32 v2, v2, v4
	v_add_u32_e32 v10, v2, v3
	v_add_u32_e32 v3, 64, v19
	s_ashr_i32 s13, s12, 31
	v_lshlrev_b32_e32 v0, 3, v18
	v_lshrrev_b32_e32 v3, 1, v3
	s_lshl_b64 s[14:15], s[12:13], 11
	v_and_b32_e32 v20, 24, v0
	v_bfe_u32 v21, v18, 4, 2
	v_lshlrev_b32_e32 v21, 3, v21
	v_xor_b32_e32 v20, v20, v21
	v_and_b32_e32 v3, 0x3fffe0, v3
	s_add_u32 s14, s24, s14
	v_add_u32_e32 v11, v2, v3
	v_lshl_or_b32 v210, v10, 10, v20
	v_mov_b32_e32 v211, v1
	s_addc_u32 s15, s25, s15
	v_lshl_or_b32 v0, v19, 10, v20
	v_lshl_or_b32 v212, v11, 10, v20
	v_lshlrev_b64 v[10:11], 1, v[210:211]
	v_mov_b32_e32 v213, v1
	v_lshl_add_u64 v[2:3], v[0:1], 1, s[14:15]
	v_add_u32_e32 v204, 0x10000, v0
	v_mov_b32_e32 v205, v1
	v_add_u32_e32 v206, 0x20000, v0
	v_mov_b32_e32 v207, v1
	v_add_u32_e32 v208, 0x30000, v0
	v_mov_b32_e32 v209, v1
	v_lshl_add_u64 v[12:13], s[6:7], 0, v[10:11]
	v_lshlrev_b64 v[14:15], 1, v[212:213]
	v_lshl_add_u64 v[4:5], v[204:205], 1, s[14:15]
	v_lshl_add_u64 v[6:7], v[206:207], 1, s[14:15]
	v_lshl_add_u64 v[8:9], v[208:209], 1, s[14:15]
	v_lshl_add_u64 v[16:17], s[6:7], 0, v[14:15]
	v_readfirstlane_b32 s18, v203
	s_nop 3
	s_lshr_b32 s18, s18, 6
	s_lshl_b32 s18, s18, 10
	v_and_b32_e32 v136, 31, v203
	v_bfe_u32 v137, v203, 5, 1
	v_bfe_u32 v138, v203, 2, 2
	v_xor_b32_e32 v137, v137, v138
	v_lshlrev_b32_e32 v137, 4, v137
	v_lshl_or_b32 v136, v136, 6, v137
	v_lshrrev_b32_e32 v138, 7, v203
	v_lshl_add_u32 v130, v138, 13, v136
	v_bfe_u32 v138, v203, 6, 1
	v_lshl_add_u32 v132, v138, 12, v136
	v_xor_b32_e32 v131, 32, v130
	v_xor_b32_e32 v133, 32, v132
	v_lshlrev_b32_e32 v139, 1, v0
	v_lshlrev_b32_e32 v140, 1, v204
	v_lshlrev_b32_e32 v141, 1, v206
	v_lshlrev_b32_e32 v142, 1, v208
	v_lshlrev_b32_e32 v143, 1, v210
	v_lshlrev_b32_e32 v144, 1, v212
	s_mov_b64 s[16:17], s[6:7]
	s_add_u32 m0, s18, 0x0
	s_nop 0
	global_load_lds_dwordx4 v139, s[14:15]
	s_add_u32 m0, s18, 0x1000
	s_nop 0
	global_load_lds_dwordx4 v140, s[14:15]
	s_add_u32 m0, s18, 0x2000
	s_nop 0
	global_load_lds_dwordx4 v141, s[14:15]
	s_add_u32 m0, s18, 0x3000
	s_nop 0
	global_load_lds_dwordx4 v142, s[14:15]
	s_add_u32 m0, s18, 0x4000
	s_nop 0
	global_load_lds_dwordx4 v143, s[16:17]
	s_add_u32 m0, s18, 0x5000
	s_nop 0
	global_load_lds_dwordx4 v144, s[16:17]
	s_add_u32 s14, s14, 64
	s_addc_u32 s15, s15, 0
	s_add_u32 s16, s16, 64
	s_addc_u32 s17, s17, 0
	v_mov_b32_e32 v2, 0
	s_mov_b32 s13, 0
	v_mov_b32_e32 v3, v2
	v_mov_b32_e32 v4, v2
	v_mov_b32_e32 v5, v2
	v_mov_b32_e32 v6, v2
	v_mov_b32_e32 v7, v2
	v_mov_b32_e32 v8, v2
	v_mov_b32_e32 v9, v2
	v_mov_b32_e32 v10, v2
	v_mov_b32_e32 v11, v2
	v_mov_b32_e32 v12, v2
	v_mov_b32_e32 v13, v2
	v_mov_b32_e32 v14, v2
	v_mov_b32_e32 v15, v2
	v_mov_b32_e32 v16, v2
	v_mov_b32_e32 v17, v2
	v_mov_b32_e32 v18, v2
	v_mov_b32_e32 v19, v2
	v_mov_b32_e32 v20, v2
	v_mov_b32_e32 v21, v2
	v_mov_b32_e32 v22, v2
	v_mov_b32_e32 v23, v2
	v_mov_b32_e32 v24, v2
	v_mov_b32_e32 v25, v2
	v_mov_b32_e32 v26, v2
	v_mov_b32_e32 v27, v2
	v_mov_b32_e32 v28, v2
	v_mov_b32_e32 v29, v2
	v_mov_b32_e32 v30, v2
	v_mov_b32_e32 v31, v2
	v_mov_b32_e32 v32, v2
	v_mov_b32_e32 v33, v2
	v_mov_b32_e32 v34, v2
	v_mov_b32_e32 v35, v2
	v_mov_b32_e32 v36, v2
	v_mov_b32_e32 v37, v2
	v_mov_b32_e32 v38, v2
	v_mov_b32_e32 v39, v2
	v_mov_b32_e32 v40, v2
	v_mov_b32_e32 v41, v2
	v_mov_b32_e32 v42, v2
	v_mov_b32_e32 v43, v2
	v_mov_b32_e32 v44, v2
	v_mov_b32_e32 v45, v2
	v_mov_b32_e32 v46, v2
	v_mov_b32_e32 v47, v2
	v_mov_b32_e32 v48, v2
	v_mov_b32_e32 v49, v2
	s_waitcnt vmcnt(15)
	v_mov_b32_e32 v50, v2
	v_mov_b32_e32 v51, v2
	v_mov_b32_e32 v52, v2
	v_mov_b32_e32 v53, v2
	s_waitcnt vmcnt(14)
	v_mov_b32_e32 v54, v2
	v_mov_b32_e32 v55, v2
	v_mov_b32_e32 v56, v2
	v_mov_b32_e32 v57, v2
	s_waitcnt vmcnt(13)
	v_mov_b32_e32 v58, v2
	v_mov_b32_e32 v59, v2
	v_mov_b32_e32 v60, v2
	v_mov_b32_e32 v61, v2
	s_waitcnt vmcnt(12)
	v_mov_b32_e32 v62, v2
	v_mov_b32_e32 v63, v2
	v_mov_b32_e32 v64, v2
	v_mov_b32_e32 v65, v2
	v_mov_b32_e32 v66, v2
	v_mov_b32_e32 v67, v2
	v_mov_b32_e32 v68, v2
	v_mov_b32_e32 v69, v2
	v_mov_b32_e32 v70, v2
	v_mov_b32_e32 v71, v2
	v_mov_b32_e32 v72, v2
	v_mov_b32_e32 v73, v2
	v_mov_b32_e32 v74, v2
	v_mov_b32_e32 v75, v2
	v_mov_b32_e32 v76, v2
	v_mov_b32_e32 v77, v2
	v_mov_b32_e32 v78, v2
	v_mov_b32_e32 v79, v2
	v_mov_b32_e32 v80, v2
	v_mov_b32_e32 v81, v2
	v_mov_b32_e32 v82, v2
	v_mov_b32_e32 v83, v2
	v_mov_b32_e32 v84, v2
	v_mov_b32_e32 v85, v2
	v_mov_b32_e32 v86, v2
	v_mov_b32_e32 v87, v2
	v_mov_b32_e32 v88, v2
	v_mov_b32_e32 v89, v2
	v_mov_b32_e32 v90, v2
	v_mov_b32_e32 v91, v2
	v_mov_b32_e32 v92, v2
	v_mov_b32_e32 v93, v2
	v_mov_b32_e32 v94, v2
	v_mov_b32_e32 v95, v2
	v_mov_b32_e32 v96, v2
	v_mov_b32_e32 v97, v2
	v_mov_b32_e32 v98, v2
	v_mov_b32_e32 v99, v2
	v_mov_b32_e32 v100, v2
	v_mov_b32_e32 v101, v2
	v_mov_b32_e32 v102, v2
	v_mov_b32_e32 v103, v2
	v_mov_b32_e32 v104, v2
	v_mov_b32_e32 v105, v2
	v_mov_b32_e32 v106, v2
	v_mov_b32_e32 v107, v2
	v_mov_b32_e32 v108, v2
	v_mov_b32_e32 v109, v2
	v_mov_b32_e32 v110, v2
	v_mov_b32_e32 v111, v2
	v_mov_b32_e32 v112, v2
	v_mov_b32_e32 v113, v2
	v_mov_b32_e32 v114, v2
	v_mov_b32_e32 v115, v2
	v_mov_b32_e32 v116, v2
	v_mov_b32_e32 v117, v2
	v_mov_b32_e32 v118, v2
	v_mov_b32_e32 v119, v2
	v_mov_b32_e32 v120, v2
	v_mov_b32_e32 v121, v2
	v_mov_b32_e32 v122, v2
	v_mov_b32_e32 v123, v2
	v_mov_b32_e32 v124, v2
	v_mov_b32_e32 v125, v2
	v_mov_b32_e32 v126, v2
	v_mov_b32_e32 v127, v2
	v_mov_b32_e32 v128, v2
	v_mov_b32_e32 v129, v2
	s_waitcnt vmcnt(0)
	s_barrier
.Lfg_stage0:
	ds_read_b128 v[178:181], v130 offset:0
	ds_read_b128 v[182:185], v130 offset:2048
	ds_read_b128 v[186:189], v130 offset:4096
	ds_read_b128 v[190:193], v130 offset:6144
	ds_read_b128 v[194:197], v132 offset:16384
	ds_read_b128 v[198:201], v132 offset:18432
	ds_read_b128 v[216:219], v131 offset:0
	ds_read_b128 v[220:223], v131 offset:2048
	ds_read_b128 v[226:229], v131 offset:4096
	ds_read_b128 v[230:233], v131 offset:6144
	ds_read_b128 v[234:237], v133 offset:16384
	ds_read_b128 v[240:243], v133 offset:18432
	s_cmp_ge_u32 s13, 31
	s_cbranch_scc1 .Lfg_nl0
	s_add_u32 m0, s18, 0x6000
	s_nop 0
	global_load_lds_dwordx4 v139, s[14:15]
	s_add_u32 m0, s18, 0x7000
	s_nop 0
	global_load_lds_dwordx4 v140, s[14:15]
	s_add_u32 m0, s18, 0x8000
	s_nop 0
	global_load_lds_dwordx4 v141, s[14:15]
	s_add_u32 m0, s18, 0x9000
	s_nop 0
	global_load_lds_dwordx4 v142, s[14:15]
	s_add_u32 m0, s18, 0xa000
	s_nop 0
	global_load_lds_dwordx4 v143, s[16:17]
	s_add_u32 m0, s18, 0xb000
	s_nop 0
	global_load_lds_dwordx4 v144, s[16:17]
	s_add_u32 s14, s14, 64
	s_addc_u32 s15, s15, 0
	s_add_u32 s16, s16, 64
	s_addc_u32 s17, s17, 0

.Lfg_stage1:
	ds_read_b128 v[178:181], v130 offset:24576
	ds_read_b128 v[182:185], v130 offset:26624
	ds_read_b128 v[186:189], v130 offset:28672
	ds_read_b128 v[190:193], v130 offset:30720
	ds_read_b128 v[194:197], v132 offset:40960
	ds_read_b128 v[198:201], v132 offset:43008
	ds_read_b128 v[216:219], v131 offset:24576
	ds_read_b128 v[220:223], v131 offset:26624
	ds_read_b128 v[226:229], v131 offset:28672
	ds_read_b128 v[230:233], v131 offset:30720
	ds_read_b128 v[234:237], v133 offset:40960
	ds_read_b128 v[240:243], v133 offset:43008
	s_cmp_ge_u32 s13, 31
	s_cbranch_scc1 .Lfg_nl1
	s_add_u32 m0, s18, 0x0
	s_nop 0
	global_load_lds_dwordx4 v139, s[14:15]
	s_add_u32 m0, s18, 0x1000
	s_nop 0
	global_load_lds_dwordx4 v140, s[14:15]
	s_add_u32 m0, s18, 0x2000
	s_nop 0
	global_load_lds_dwordx4 v141, s[14:15]
	s_add_u32 m0, s18, 0x3000
	s_nop 0
	global_load_lds_dwordx4 v142, s[14:15]
	s_add_u32 m0, s18, 0x4000
	s_nop 0
	global_load_lds_dwordx4 v143, s[16:17]
	s_add_u32 m0, s18, 0x5000
	s_nop 0
	global_load_lds_dwordx4 v144, s[16:17]
	s_add_u32 s14, s14, 64
	s_addc_u32 s15, s15, 0
	s_add_u32 s16, s16, 64
	s_addc_u32 s17, s17, 0

; DI int TIDX() { int t = threadIdx.x; asm volatile("" : "+v"(t)); return t; }
; DI void gemm_tile_deep(const h16* __restrict__ A, int lda, const h16* __restrict__ B, int ldb, int K, f32x16 (&acc)[2][2], h16* sm) {
;   const int tid = TIDX(), lane = tid & 63, w = tid >> 6, wm = w >> 1, wn = w & 1, r = lane & 31, hh = lane >> 5;
;   const unsigned ao = (unsigned)(tid >> 3) * (unsigned)lda + (unsigned)(tid & 7) * 8u;
;   const unsigned bo = (unsigned)(tid >> 3) * (unsigned)ldb + (unsigned)(tid & 7) * 8u;
;   const h16* ag = A;
;   const h16* bg = B;
;   u32x4 ra0[4], rb0[4], ra1[4], rb1[4];
; #pragma unroll
;   for (int i = 0; i < 4; ++i) {
;     ra0[i] = *(const u32x4*)(ag + (ao + (unsigned)i * 32u * (unsigned)lda));
;     rb0[i] = *(const u32x4*)(bg + (bo + (unsigned)i * 32u * (unsigned)ldb));
;   }
;   ag += 64; bg += 64;
; #pragma unroll
;   for (int i = 0; i < 4; ++i) {
;     ra1[i] = *(const u32x4*)(ag + (ao + (unsigned)i * 32u * (unsigned)lda));
;     rb1[i] = *(const u32x4*)(bg + (bo + (unsigned)i * 32u * (unsigned)ldb));
;   }
;   const int nk = K >> 6;
;   const int wofs = (tid >> 3) * LSTR + (tid & 7) * 8;
.LBB0_91:
	s_ashr_i32 s4, s15, 31
	s_lshr_b32 s4, s4, 26
	s_add_i32 s4, s15, s4
	s_ashr_i32 s5, s4, 6
	s_lshl_b32 s5, s5, 3
	s_sub_i32 s6, s20, s5
	s_min_i32 s6, s6, 8
	s_abs_i32 s7, s6
	v_cvt_f32_u32_e32 v0, s7
	s_sub_i32 s10, 0, s7
	s_andn2_b32 s4, s4, 63
	s_sub_i32 s4, s15, s4
	v_rcp_iflag_f32_e32 v0, v0
	s_abs_i32 s8, s4
	s_xor_b32 s9, s4, s6
	s_ashr_i32 s9, s9, 31
	v_mul_f32_e32 v0, 0x4f7ffffe, v0
	v_cvt_u32_f32_e32 v0, v0
	v_mov_b32_e32 v18, v203
	v_mov_b32_e32 v7, v1
	v_readfirstlane_b32 s11, v0
	s_mul_i32 s10, s10, s11
	s_mul_hi_u32 s10, s11, s10
	s_add_i32 s11, s11, s10
	s_mul_hi_u32 s10, s8, s11
	s_mul_i32 s11, s10, s7
	s_sub_i32 s8, s8, s11
	s_add_i32 s12, s10, 1
	s_sub_i32 s11, s8, s7
	s_cmp_ge_u32 s8, s7
	s_cselect_b32 s10, s12, s10
	s_cselect_b32 s8, s11, s8
	s_add_i32 s11, s10, 1
	s_cmp_ge_u32 s8, s7
	s_cselect_b32 s7, s11, s10
	s_xor_b32 s7, s7, s9
	s_sub_i32 s7, s7, s9
	s_add_i32 s5, s5, s21
	s_mul_i32 s6, s6, s7
	s_add_i32 s5, s5, s4
	s_sub_i32 s4, s5, s6
	s_lshl_b32 s6, s4, 7
	s_lshl_b32 s4, s7, 7
	s_ashr_i32 s7, s6, 31
	s_lshl_b64 s[8:9], s[6:7], 11
	s_add_u32 s10, s16, s8
	v_lshlrev_b32_e32 v0, 3, v18
	s_addc_u32 s11, s17, s9
	s_ashr_i32 s5, s4, 31
	v_ashrrev_i32_e32 v19, 3, v18
	v_and_b32_e32 v20, 56, v0
	v_bfe_u32 v21, v18, 4, 3
	v_lshlrev_b32_e32 v21, 3, v21
	v_xor_b32_e32 v20, v20, v21
	s_lshl_b64 s[8:9], s[4:5], 11
	v_lshl_or_b32 v0, v19, 10, v20
	s_add_u32 s8, s18, s8
	v_add_u32_e32 v6, 0x18000, v0
	s_addc_u32 s9, s19, s9
	v_add_u32_e32 v2, 0x8000, v0
	v_mov_b32_e32 v3, v1
	v_add_u32_e32 v4, 0x10000, v0
	v_mov_b32_e32 v5, v1
	s_waitcnt vmcnt(0)
	v_lshlrev_b64 v[146:147], 1, v[6:7]
	v_lshl_add_u64 v[6:7], s[8:9], 0, v[146:147]
	v_lshlrev_b64 v[148:149], 1, v[4:5]
	v_lshlrev_b64 v[150:151], 1, v[2:3]
	v_lshlrev_b64 v[152:153], 1, v[0:1]
	v_lshl_add_u64 v[8:9], s[10:11], 0, v[146:147]
	v_lshl_add_u64 v[4:5], s[8:9], 0, v[148:149]
	v_lshl_add_u64 v[10:11], s[10:11], 0, v[148:149]
	v_lshl_add_u64 v[2:3], s[8:9], 0, v[150:151]
	v_lshl_add_u64 v[12:13], s[10:11], 0, v[150:151]
	v_lshl_add_u64 v[14:15], s[8:9], 0, v[152:153]
	v_lshl_add_u64 v[16:17], s[10:11], 0, v[152:153]
	v_readfirstlane_b32 s38, v203
	s_nop 3
	s_lshr_b32 s38, s38, 6
	s_lshl_b32 s38, s38, 10
	v_and_b32_e32 v140, 31, v203
	v_bfe_u32 v141, v203, 5, 1
	v_bfe_u32 v142, v203, 1, 3
	v_xor_b32_e32 v141, v141, v142
	v_lshlrev_b32_e32 v141, 4, v141
	v_lshl_or_b32 v140, v140, 7, v141
	v_lshrrev_b32_e32 v142, 7, v203
	v_lshl_add_u32 v130, v142, 13, v140
	v_bfe_u32 v142, v203, 6, 1
	v_lshl_add_u32 v134, v142, 13, v140
	v_xor_b32_e32 v131, 0x20, v130
	v_xor_b32_e32 v135, 0x20, v134
	v_xor_b32_e32 v132, 0x40, v130
	v_xor_b32_e32 v136, 0x40, v134
	v_xor_b32_e32 v133, 0x60, v130
	v_xor_b32_e32 v137, 0x60, v134
	s_add_u32 m0, s38, 0x0
	s_nop 0
	global_load_lds_dwordx4 v152, s[10:11]
	s_add_u32 m0, s38, 0x4000
	s_nop 0
	global_load_lds_dwordx4 v152, s[8:9]
	s_add_u32 m0, s38, 0x1000
	s_nop 0
	global_load_lds_dwordx4 v150, s[10:11]
	s_add_u32 m0, s38, 0x5000
	s_nop 0
	global_load_lds_dwordx4 v150, s[8:9]
	s_add_u32 m0, s38, 0x2000
	s_nop 0
	global_load_lds_dwordx4 v148, s[10:11]
	s_add_u32 m0, s38, 0x6000
	s_nop 0
	global_load_lds_dwordx4 v148, s[8:9]
	s_add_u32 m0, s38, 0x3000
	s_nop 0
	global_load_lds_dwordx4 v146, s[10:11]
	s_add_u32 m0, s38, 0x7000
	s_nop 0
	global_load_lds_dwordx4 v146, s[8:9]
	s_add_u32 s8, s8, 0x80
	s_addc_u32 s9, s9, 0
	s_add_u32 s10, s10, 0x80
	s_addc_u32 s11, s11, 0
	v_mov_b32_e32 v2, 0
	s_mov_b32 s22, 0
	v_mov_b32_e32 v3, v2
	v_mov_b32_e32 v4, v2
	v_mov_b32_e32 v5, v2
	v_mov_b32_e32 v6, v2
	v_mov_b32_e32 v7, v2
	v_mov_b32_e32 v8, v2
	v_mov_b32_e32 v9, v2
	v_mov_b32_e32 v10, v2
	v_mov_b32_e32 v11, v2
	v_mov_b32_e32 v12, v2
	v_mov_b32_e32 v13, v2
	v_mov_b32_e32 v14, v2
	v_mov_b32_e32 v15, v2
	v_mov_b32_e32 v16, v2
	v_mov_b32_e32 v17, v2
	v_mov_b32_e32 v18, v2
	v_mov_b32_e32 v19, v2
	v_mov_b32_e32 v20, v2
	v_mov_b32_e32 v21, v2
	v_mov_b32_e32 v22, v2
	v_mov_b32_e32 v23, v2
	v_mov_b32_e32 v24, v2
	v_mov_b32_e32 v25, v2
	v_mov_b32_e32 v26, v2
	v_mov_b32_e32 v27, v2
	v_mov_b32_e32 v28, v2
	v_mov_b32_e32 v29, v2
	v_mov_b32_e32 v30, v2
	v_mov_b32_e32 v31, v2
	v_mov_b32_e32 v32, v2
	v_mov_b32_e32 v33, v2
	v_mov_b32_e32 v34, v2
	v_mov_b32_e32 v35, v2
	v_mov_b32_e32 v36, v2
	v_mov_b32_e32 v37, v2
	v_mov_b32_e32 v38, v2
	v_mov_b32_e32 v39, v2
	v_mov_b32_e32 v40, v2
	v_mov_b32_e32 v41, v2
	v_mov_b32_e32 v42, v2
	v_mov_b32_e32 v43, v2
	v_mov_b32_e32 v44, v2
	v_mov_b32_e32 v45, v2
	v_mov_b32_e32 v46, v2
	v_mov_b32_e32 v47, v2
	v_mov_b32_e32 v48, v2
	v_mov_b32_e32 v49, v2
	v_mov_b32_e32 v50, v2
	v_mov_b32_e32 v51, v2
	v_mov_b32_e32 v52, v2
	v_mov_b32_e32 v53, v2
	v_mov_b32_e32 v54, v2
	v_mov_b32_e32 v55, v2
	v_mov_b32_e32 v56, v2
	v_mov_b32_e32 v57, v2
	v_mov_b32_e32 v58, v2
	v_mov_b32_e32 v59, v2
	v_mov_b32_e32 v60, v2
	v_mov_b32_e32 v61, v2
	v_mov_b32_e32 v62, v2
	v_mov_b32_e32 v63, v2
	v_mov_b32_e32 v64, v2
	v_mov_b32_e32 v65, v2
	s_waitcnt vmcnt(0)
	s_barrier
.Lwo_stage0:
	ds_read_b128 v[66:69], v130 offset:0
	ds_read_b128 v[70:73], v130 offset:4096
	ds_read_b128 v[74:77], v134 offset:16384
	ds_read_b128 v[78:81], v134 offset:20480
	ds_read_b128 v[82:85], v131 offset:0
	ds_read_b128 v[86:89], v131 offset:4096
	ds_read_b128 v[90:93], v135 offset:16384
	ds_read_b128 v[94:97], v135 offset:20480
	ds_read_b128 v[98:101], v132 offset:0
	ds_read_b128 v[102:105], v132 offset:4096
	ds_read_b128 v[106:109], v136 offset:16384
	ds_read_b128 v[110:113], v136 offset:20480
	s_cmp_ge_u32 s22, 15
	s_cbranch_scc1 .Lwo_nl0
	s_add_u32 m0, s38, 0x8000
	s_nop 0
	global_load_lds_dwordx4 v152, s[10:11]
	s_add_u32 m0, s38, 0xc000
	s_nop 0
	global_load_lds_dwordx4 v152, s[8:9]
	s_add_u32 m0, s38, 0x9000
	s_nop 0
	global_load_lds_dwordx4 v150, s[10:11]
	s_add_u32 m0, s38, 0xd000
	s_nop 0
	global_load_lds_dwordx4 v150, s[8:9]
	s_add_u32 m0, s38, 0xa000
	s_nop 0
	global_load_lds_dwordx4 v148, s[10:11]
	s_add_u32 m0, s38, 0xe000
	s_nop 0
	global_load_lds_dwordx4 v148, s[8:9]
	s_add_u32 m0, s38, 0xb000
	s_nop 0
	global_load_lds_dwordx4 v146, s[10:11]
	s_add_u32 m0, s38, 0xf000
	s_nop 0
	global_load_lds_dwordx4 v146, s[8:9]
	s_add_u32 s8, s8, 0x80
	s_addc_u32 s9, s9, 0
	s_add_u32 s10, s10, 0x80
	s_addc_u32 s11, s11, 0

.Lwo_stage1:
	ds_read_b128 v[66:69], v130 offset:32768
	ds_read_b128 v[70:73], v130 offset:36864
	ds_read_b128 v[74:77], v134 offset:49152
	ds_read_b128 v[78:81], v134 offset:53248
	ds_read_b128 v[82:85], v131 offset:32768
	ds_read_b128 v[86:89], v131 offset:36864
	ds_read_b128 v[90:93], v135 offset:49152
	ds_read_b128 v[94:97], v135 offset:53248
	ds_read_b128 v[98:101], v132 offset:32768
	ds_read_b128 v[102:105], v132 offset:36864
	ds_read_b128 v[106:109], v136 offset:49152
	ds_read_b128 v[110:113], v136 offset:53248
	s_cmp_ge_u32 s22, 15
	s_cbranch_scc1 .Lwo_nl1
	s_add_u32 m0, s38, 0x0
	s_nop 0
	global_load_lds_dwordx4 v152, s[10:11]
	s_add_u32 m0, s38, 0x4000
	s_nop 0
	global_load_lds_dwordx4 v152, s[8:9]
	s_add_u32 m0, s38, 0x1000
	s_nop 0
	global_load_lds_dwordx4 v150, s[10:11]
	s_add_u32 m0, s38, 0x5000
	s_nop 0
	global_load_lds_dwordx4 v150, s[8:9]
	s_add_u32 m0, s38, 0x2000
	s_nop 0
	global_load_lds_dwordx4 v148, s[10:11]
	s_add_u32 m0, s38, 0x6000
	s_nop 0
	global_load_lds_dwordx4 v148, s[8:9]
	s_add_u32 m0, s38, 0x3000
	s_nop 0
	global_load_lds_dwordx4 v146, s[10:11]
	s_add_u32 m0, s38, 0x7000
	s_nop 0
	global_load_lds_dwordx4 v146, s[8:9]
	s_add_u32 s8, s8, 0x80
	s_addc_u32 s9, s9, 0
	s_add_u32 s10, s10, 0x80
	s_addc_u32 s11, s11, 0

; DI int TIDX() { int t = threadIdx.x; asm volatile("" : "+v"(t)); return t; }
; #define XCD_LOOP_W(Mt, ntn) const int xcd_ = BIDX() & 7; const int Mx_ = ((Mt) + 7) >> 3; for (int u_ = BIDX() >> 3; u_ < Mx_ * (ntn); u_ += (int)(gridDim.x >> 3))
; template <class BR>
; DI void gemm_tile_w(const h16* __restrict__ A, int lda, const h16* __restrict__ B, int ldb, BR brow, int K, f32x16 (&acc)[4][2], h16* sm) {
;   const int tid = TIDX(), lane = tid & 63, w = tid >> 6, wm = w >> 1, wn = w & 1, r = lane & 31, hh = lane >> 5;
;   const unsigned ao = (unsigned)(tid >> 2) * (unsigned)lda + (unsigned)(tid & 3) * 8u;
;   const unsigned bo0 = (unsigned)brow(tid >> 2) * (unsigned)ldb + (unsigned)(tid & 3) * 8u;
;   const unsigned bo1 = (unsigned)brow((tid >> 2) + 64) * (unsigned)ldb + (unsigned)(tid & 3) * 8u;
;   const h16* ag = A;
;   const h16* bg = B;
;   u32x4 ra0[4], rb0[2], ra1[4], rb1[2];
; #pragma unroll
;   for (int i = 0; i < 4; ++i) ra0[i] = *(const u32x4*)(ag + (ao + (unsigned)i * 64u * (unsigned)lda));
;   rb0[0] = *(const u32x4*)(bg + bo0);
;   rb0[1] = *(const u32x4*)(bg + bo1);
;   ag += 32; bg += 32;
; #pragma unroll
;   for (int i = 0; i < 4; ++i) ra1[i] = *(const u32x4*)(ag + (ao + (unsigned)i * 64u * (unsigned)lda));
;   rb1[0] = *(const u32x4*)(bg + bo0);
;   rb1[1] = *(const u32x4*)(bg + bo1);
;   const int nk = K >> 5;
;   const int wofs = (tid >> 2) * LS2 + (tid & 3) * 8;
; DI void phase_proj(const P& p, int l, char* smem) {
;     ...
;   XCD_LOOP_W(136, 27) {
;     int mt_, nt_;
;     tile_map(u_, Mx_, 27, xcd_, mt_, nt_);
;     if (mt_ >= 136) continue;
;     const int m0 = mt_ * 256, n0 = nt_ * 128;
;     f32x16 acc[4][2];
;     zero_acc_w(acc);
;     gemm_tile_w(hbuf + (size_t)m0 * 1024, 1024, W, 1024, [&](int rr) { return n0 + rr; }, 1024, acc, (h16*)smem);
.LBB0_693:
	s_mul_hi_i32 s0, s36, 0x4bda12f7
	s_lshr_b32 s1, s0, 31
	s_ashr_i32 s0, s0, 6
	s_add_i32 s0, s0, s1
	s_lshl_b32 s4, s0, 3
	s_sub_i32 s1, 17, s4
	s_min_u32 s5, s1, 8
	v_cvt_f32_ubyte0_e32 v0, s5
	v_rcp_iflag_f32_e32 v0, v0
	s_sub_i32 s7, 0, s5
	s_mulk_i32 s0, 0xff28
	s_add_i32 s0, s0, s36
	v_mul_f32_e32 v0, 0x4f7ffffe, v0
	v_cvt_u32_f32_e32 v0, v0
	s_abs_i32 s6, s0
	s_ashr_i32 s1, s0, 31
	v_readfirstlane_b32 s8, v0
	s_mul_i32 s7, s7, s8
	s_mul_hi_u32 s7, s8, s7
	s_add_i32 s8, s8, s7
	s_mul_hi_u32 s7, s6, s8
	s_mul_i32 s8, s7, s5
	s_sub_i32 s6, s6, s8
	s_add_i32 s8, s7, 1
	s_sub_i32 s9, s6, s5
	s_cmp_ge_u32 s6, s5
	s_cselect_b32 s7, s8, s7
	s_cselect_b32 s6, s9, s6
	s_add_i32 s8, s7, 1
	s_cmp_ge_u32 s6, s5
	s_cselect_b32 s6, s8, s7
	s_xor_b32 s6, s6, s1
	s_sub_i32 s1, s6, s1
	s_add_i32 s4, s4, s72
	s_mul_i32 s5, s5, s1
	s_add_i32 s4, s4, s0
	s_sub_i32 s0, s4, s5
	s_cmpk_gt_i32 s0, 0x87
	s_cbranch_scc1 .LBB0_692
	s_lshl_b32 s0, s0, 8
	s_lshl_b32 s10, s1, 7
	s_ashr_i32 s1, s0, 31
	v_mov_b32_e32 v14, v203
	s_lshl_b64 s[4:5], s[0:1], 11
	s_add_u32 s4, s69, s4
	v_ashrrev_i32_e32 v15, 2, v14
	v_lshlrev_b32_e32 v0, 3, v14
	v_and_b32_e32 v16, 24, v0
	v_bfe_u32 v17, v14, 4, 2
	v_lshlrev_b32_e32 v17, 3, v17
	v_xor_b32_e32 v16, v16, v17
	v_add_u32_e32 v10, s10, v15
	s_addc_u32 s5, s24, s5
	v_lshl_or_b32 v0, v15, 10, v16
	v_lshl_or_b32 v210, v10, 10, v16
	v_lshl_add_u64 v[2:3], v[0:1], 1, s[4:5]
	v_add_u32_e32 v204, 0x10000, v0
	v_mov_b32_e32 v205, v1
	v_add_u32_e32 v206, 0x20000, v0
	v_mov_b32_e32 v207, v1
	v_add_u32_e32 v208, 0x30000, v0
	v_mov_b32_e32 v209, v1
	v_add_u32_e32 v212, 0x10000, v210
	v_mov_b32_e32 v211, v1
	s_mov_b64 s[6:7], s[54:55]
	v_mov_b32_e32 v213, v1
	v_lshl_add_u64 v[4:5], v[204:205], 1, s[4:5]
	v_lshl_add_u64 v[6:7], v[206:207], 1, s[4:5]
	v_lshl_add_u64 v[8:9], v[208:209], 1, s[4:5]
	v_lshl_add_u64 v[10:11], v[210:211], 1, s[6:7]
	v_lshl_add_u64 v[12:13], v[212:213], 1, s[6:7]
	v_readfirstlane_b32 s18, v203
	s_nop 3
	s_lshr_b32 s18, s18, 6
	s_lshl_b32 s18, s18, 10
	v_and_b32_e32 v136, 31, v203
	v_bfe_u32 v137, v203, 5, 1
	v_bfe_u32 v138, v203, 2, 2
	v_xor_b32_e32 v137, v137, v138
	v_lshlrev_b32_e32 v137, 4, v137
	v_lshl_or_b32 v136, v136, 6, v137
	v_lshrrev_b32_e32 v138, 7, v203
	v_lshl_add_u32 v130, v138, 13, v136
	v_bfe_u32 v138, v203, 6, 1
	v_lshl_add_u32 v132, v138, 12, v136
	v_xor_b32_e32 v131, 32, v130
	v_xor_b32_e32 v133, 32, v132
	v_lshlrev_b32_e32 v139, 1, v0
	v_lshlrev_b32_e32 v140, 1, v204
	v_lshlrev_b32_e32 v141, 1, v206
	v_lshlrev_b32_e32 v142, 1, v208
	v_lshlrev_b32_e32 v143, 1, v210
	v_lshlrev_b32_e32 v144, 1, v212
	s_add_u32 m0, s18, 0x0
	s_nop 0
	global_load_lds_dwordx4 v139, s[4:5]
	s_add_u32 m0, s18, 0x1000
	s_nop 0
	global_load_lds_dwordx4 v140, s[4:5]
	s_add_u32 m0, s18, 0x2000
	s_nop 0
	global_load_lds_dwordx4 v141, s[4:5]
	s_add_u32 m0, s18, 0x3000
	s_nop 0
	global_load_lds_dwordx4 v142, s[4:5]
	s_add_u32 m0, s18, 0x4000
	s_nop 0
	global_load_lds_dwordx4 v143, s[6:7]
	s_add_u32 m0, s18, 0x5000
	s_nop 0
	global_load_lds_dwordx4 v144, s[6:7]
	s_add_u32 s4, s4, 64
	s_addc_u32 s5, s5, 0
	s_add_u32 s6, s6, 64
	s_addc_u32 s7, s7, 0
	v_mov_b32_e32 v114, 0
	s_mov_b32 s1, 0
	v_mov_b32_e32 v115, v114
	v_mov_b32_e32 v116, v114
	s_waitcnt vmcnt(14)
	v_mov_b32_e32 v117, v114
	v_mov_b32_e32 v118, v114
	v_mov_b32_e32 v119, v114
	s_waitcnt vmcnt(13)
	v_mov_b32_e32 v120, v114
	v_mov_b32_e32 v121, v114
	v_mov_b32_e32 v122, v114
	s_waitcnt vmcnt(12)
	v_mov_b32_e32 v123, v114
	v_mov_b32_e32 v124, v114
	v_mov_b32_e32 v125, v114
	v_mov_b32_e32 v126, v114
	v_mov_b32_e32 v127, v114
	v_mov_b32_e32 v128, v114
	v_mov_b32_e32 v129, v114
	v_mov_b32_e32 v98, v114
	v_mov_b32_e32 v99, v114
	v_mov_b32_e32 v100, v114
	v_mov_b32_e32 v101, v114
	v_mov_b32_e32 v102, v114
	v_mov_b32_e32 v103, v114
	v_mov_b32_e32 v104, v114
	v_mov_b32_e32 v105, v114
	v_mov_b32_e32 v106, v114
	v_mov_b32_e32 v107, v114
	v_mov_b32_e32 v108, v114
	v_mov_b32_e32 v109, v114
	v_mov_b32_e32 v110, v114
	v_mov_b32_e32 v111, v114
	v_mov_b32_e32 v112, v114
	v_mov_b32_e32 v113, v114
	v_mov_b32_e32 v82, v114
	v_mov_b32_e32 v83, v114
	v_mov_b32_e32 v84, v114
	v_mov_b32_e32 v85, v114
	v_mov_b32_e32 v86, v114
	v_mov_b32_e32 v87, v114
	v_mov_b32_e32 v88, v114
	v_mov_b32_e32 v89, v114
	v_mov_b32_e32 v90, v114
	v_mov_b32_e32 v91, v114
	v_mov_b32_e32 v92, v114
	v_mov_b32_e32 v93, v114
	v_mov_b32_e32 v94, v114
	v_mov_b32_e32 v95, v114
	v_mov_b32_e32 v96, v114
	v_mov_b32_e32 v97, v114
	v_mov_b32_e32 v66, v114
	v_mov_b32_e32 v67, v114
	v_mov_b32_e32 v68, v114
	v_mov_b32_e32 v69, v114
	v_mov_b32_e32 v70, v114
	v_mov_b32_e32 v71, v114
	v_mov_b32_e32 v72, v114
	v_mov_b32_e32 v73, v114
	v_mov_b32_e32 v74, v114
	v_mov_b32_e32 v75, v114
	v_mov_b32_e32 v76, v114
	v_mov_b32_e32 v77, v114
	v_mov_b32_e32 v78, v114
	v_mov_b32_e32 v79, v114
	v_mov_b32_e32 v80, v114
	v_mov_b32_e32 v81, v114
	v_mov_b32_e32 v50, v114
	v_mov_b32_e32 v51, v114
	v_mov_b32_e32 v52, v114
	v_mov_b32_e32 v53, v114
	v_mov_b32_e32 v54, v114
	v_mov_b32_e32 v55, v114
	v_mov_b32_e32 v56, v114
	v_mov_b32_e32 v57, v114
	v_mov_b32_e32 v58, v114
	v_mov_b32_e32 v59, v114
	v_mov_b32_e32 v60, v114
	v_mov_b32_e32 v61, v114
	v_mov_b32_e32 v62, v114
	v_mov_b32_e32 v63, v114
	v_mov_b32_e32 v64, v114
	v_mov_b32_e32 v65, v114
	v_mov_b32_e32 v34, v114
	v_mov_b32_e32 v35, v114
	v_mov_b32_e32 v36, v114
	v_mov_b32_e32 v37, v114
	v_mov_b32_e32 v38, v114
	v_mov_b32_e32 v39, v114
	v_mov_b32_e32 v40, v114
	v_mov_b32_e32 v41, v114
	v_mov_b32_e32 v42, v114
	v_mov_b32_e32 v43, v114
	v_mov_b32_e32 v44, v114
	v_mov_b32_e32 v45, v114
	v_mov_b32_e32 v46, v114
	v_mov_b32_e32 v47, v114
	v_mov_b32_e32 v48, v114
	v_mov_b32_e32 v49, v114
	v_mov_b32_e32 v18, v114
	v_mov_b32_e32 v19, v114
	v_mov_b32_e32 v20, v114
	v_mov_b32_e32 v21, v114
	v_mov_b32_e32 v22, v114
	v_mov_b32_e32 v23, v114
	v_mov_b32_e32 v24, v114
	v_mov_b32_e32 v25, v114
	v_mov_b32_e32 v26, v114
	v_mov_b32_e32 v27, v114
	v_mov_b32_e32 v28, v114
	v_mov_b32_e32 v29, v114
	v_mov_b32_e32 v30, v114
	v_mov_b32_e32 v31, v114
	v_mov_b32_e32 v32, v114
	v_mov_b32_e32 v33, v114
	v_mov_b32_e32 v2, v114
	v_mov_b32_e32 v3, v114
	v_mov_b32_e32 v4, v114
	v_mov_b32_e32 v5, v114
	v_mov_b32_e32 v6, v114
	v_mov_b32_e32 v7, v114
	v_mov_b32_e32 v8, v114
	v_mov_b32_e32 v9, v114
	v_mov_b32_e32 v10, v114
	v_mov_b32_e32 v11, v114
	v_mov_b32_e32 v12, v114
	v_mov_b32_e32 v13, v114
	v_mov_b32_e32 v14, v114
	v_mov_b32_e32 v15, v114
	v_mov_b32_e32 v16, v114
	v_mov_b32_e32 v17, v114
	s_waitcnt vmcnt(0)
	s_barrier
.Lpg_stage0:
	ds_read_b128 v[178:181], v130 offset:0
	ds_read_b128 v[182:185], v130 offset:2048
	ds_read_b128 v[186:189], v130 offset:4096
	ds_read_b128 v[190:193], v130 offset:6144
	ds_read_b128 v[194:197], v132 offset:16384
	ds_read_b128 v[198:201], v132 offset:18432
	ds_read_b128 v[216:219], v131 offset:0
	ds_read_b128 v[220:223], v131 offset:2048
	ds_read_b128 v[226:229], v131 offset:4096
	ds_read_b128 v[230:233], v131 offset:6144
	ds_read_b128 v[234:237], v133 offset:16384
	ds_read_b128 v[240:243], v133 offset:18432
	s_cmp_ge_u32 s1, 31
	s_cbranch_scc1 .Lpg_nl0
	s_add_u32 m0, s18, 0x6000
	s_nop 0
	global_load_lds_dwordx4 v139, s[4:5]
	s_add_u32 m0, s18, 0x7000
	s_nop 0
	global_load_lds_dwordx4 v140, s[4:5]
	s_add_u32 m0, s18, 0x8000
	s_nop 0
	global_load_lds_dwordx4 v141, s[4:5]
	s_add_u32 m0, s18, 0x9000
	s_nop 0
	global_load_lds_dwordx4 v142, s[4:5]
	s_add_u32 m0, s18, 0xa000
	s_nop 0
	global_load_lds_dwordx4 v143, s[6:7]
	s_add_u32 m0, s18, 0xb000
	s_nop 0
	global_load_lds_dwordx4 v144, s[6:7]
	s_add_u32 s4, s4, 64
	s_addc_u32 s5, s5, 0
	s_add_u32 s6, s6, 64
	s_addc_u32 s7, s7, 0

.Lpg_stage1:
	ds_read_b128 v[178:181], v130 offset:24576
	ds_read_b128 v[182:185], v130 offset:26624
	ds_read_b128 v[186:189], v130 offset:28672
	ds_read_b128 v[190:193], v130 offset:30720
	ds_read_b128 v[194:197], v132 offset:40960
	ds_read_b128 v[198:201], v132 offset:43008
	ds_read_b128 v[216:219], v131 offset:24576
	ds_read_b128 v[220:223], v131 offset:26624
	ds_read_b128 v[226:229], v131 offset:28672
	ds_read_b128 v[230:233], v131 offset:30720
	ds_read_b128 v[234:237], v133 offset:40960
	ds_read_b128 v[240:243], v133 offset:43008
	s_cmp_ge_u32 s1, 31
	s_cbranch_scc1 .Lpg_nl1
	s_add_u32 m0, s18, 0x0
	s_nop 0
	global_load_lds_dwordx4 v139, s[4:5]
	s_add_u32 m0, s18, 0x1000
	s_nop 0
	global_load_lds_dwordx4 v140, s[4:5]
	s_add_u32 m0, s18, 0x2000
	s_nop 0
	global_load_lds_dwordx4 v141, s[4:5]
	s_add_u32 m0, s18, 0x3000
	s_nop 0
	global_load_lds_dwordx4 v142, s[4:5]
	s_add_u32 m0, s18, 0x4000
	s_nop 0
	global_load_lds_dwordx4 v143, s[6:7]
	s_add_u32 m0, s18, 0x5000
	s_nop 0
	global_load_lds_dwordx4 v144, s[6:7]
	s_add_u32 s4, s4, 64
	s_addc_u32 s5, s5, 0
	s_add_u32 s6, s6, 64
	s_addc_u32 s7, s7, 0
